# adaLN phase-0 loop: ring of 32 in-flight w loads per wave + double-buffered LDS sv reads
# baseline (speedup 1.0000x reference)
.LBB0_565:
	s_movk_i32 s24, 0x3000
	s_mov_b32 s25, 0
	v_mov_b32_e32 v54, v4
	v_mov_b32_e32 v55, v5
	v_mov_b32_e32 v17, s3
	global_load_dword v70, v[54:55], off
	v_lshl_add_u64 v[54:55], v[54:55], 0, s[24:25]
	global_load_dword v71, v[54:55], off
	v_lshl_add_u64 v[54:55], v[54:55], 0, s[24:25]
	global_load_dword v72, v[54:55], off
	v_lshl_add_u64 v[54:55], v[54:55], 0, s[24:25]
	global_load_dword v73, v[54:55], off
	v_lshl_add_u64 v[54:55], v[54:55], 0, s[24:25]
	global_load_dword v74, v[54:55], off
	v_lshl_add_u64 v[54:55], v[54:55], 0, s[24:25]
	global_load_dword v75, v[54:55], off
	v_lshl_add_u64 v[54:55], v[54:55], 0, s[24:25]
	global_load_dword v76, v[54:55], off
	v_lshl_add_u64 v[54:55], v[54:55], 0, s[24:25]
	global_load_dword v77, v[54:55], off
	v_lshl_add_u64 v[54:55], v[54:55], 0, s[24:25]
	global_load_dword v78, v[54:55], off
	v_lshl_add_u64 v[54:55], v[54:55], 0, s[24:25]
	global_load_dword v79, v[54:55], off
	v_lshl_add_u64 v[54:55], v[54:55], 0, s[24:25]
	global_load_dword v80, v[54:55], off
	v_lshl_add_u64 v[54:55], v[54:55], 0, s[24:25]
	global_load_dword v81, v[54:55], off
	v_lshl_add_u64 v[54:55], v[54:55], 0, s[24:25]
	global_load_dword v82, v[54:55], off
	v_lshl_add_u64 v[54:55], v[54:55], 0, s[24:25]
	global_load_dword v83, v[54:55], off
	v_lshl_add_u64 v[54:55], v[54:55], 0, s[24:25]
	global_load_dword v84, v[54:55], off
	v_lshl_add_u64 v[54:55], v[54:55], 0, s[24:25]
	global_load_dword v85, v[54:55], off
	v_lshl_add_u64 v[54:55], v[54:55], 0, s[24:25]
	global_load_dword v86, v[54:55], off
	v_lshl_add_u64 v[54:55], v[54:55], 0, s[24:25]
	global_load_dword v87, v[54:55], off
	v_lshl_add_u64 v[54:55], v[54:55], 0, s[24:25]
	global_load_dword v88, v[54:55], off
	v_lshl_add_u64 v[54:55], v[54:55], 0, s[24:25]
	global_load_dword v89, v[54:55], off
	v_lshl_add_u64 v[54:55], v[54:55], 0, s[24:25]
	global_load_dword v90, v[54:55], off
	v_lshl_add_u64 v[54:55], v[54:55], 0, s[24:25]
	global_load_dword v91, v[54:55], off
	v_lshl_add_u64 v[54:55], v[54:55], 0, s[24:25]
	global_load_dword v92, v[54:55], off
	v_lshl_add_u64 v[54:55], v[54:55], 0, s[24:25]
	global_load_dword v93, v[54:55], off
	v_lshl_add_u64 v[54:55], v[54:55], 0, s[24:25]
	global_load_dword v94, v[54:55], off
	v_lshl_add_u64 v[54:55], v[54:55], 0, s[24:25]
	global_load_dword v95, v[54:55], off
	v_lshl_add_u64 v[54:55], v[54:55], 0, s[24:25]
	global_load_dword v96, v[54:55], off
	v_lshl_add_u64 v[54:55], v[54:55], 0, s[24:25]
	global_load_dword v97, v[54:55], off
	v_lshl_add_u64 v[54:55], v[54:55], 0, s[24:25]
	global_load_dword v98, v[54:55], off
	v_lshl_add_u64 v[54:55], v[54:55], 0, s[24:25]
	global_load_dword v99, v[54:55], off
	v_lshl_add_u64 v[54:55], v[54:55], 0, s[24:25]
	global_load_dword v100, v[54:55], off
	v_lshl_add_u64 v[54:55], v[54:55], 0, s[24:25]
	global_load_dword v101, v[54:55], off
	v_lshl_add_u64 v[54:55], v[54:55], 0, s[24:25]
	ds_read_b128 v[46:49], v17
	ds_read_b128 v[18:21], v17 offset:4096
	ds_read_b128 v[22:25], v17 offset:8192
	ds_read_b128 v[26:29], v17 offset:12288
	ds_read_b128 v[30:33], v17 offset:16384
	ds_read_b128 v[34:37], v17 offset:20480
	ds_read_b128 v[38:41], v17 offset:24576
	ds_read_b128 v[42:45], v17 offset:28672
	ds_read_b128 v[50:53], v17 offset:32768
	s_mov_b32 s4, 3
.Lada_loop:
	v_add_u32_e32 v17, 16, v17
	ds_read_b128 v[56:59], v17
	ds_read_b128 v[60:63], v17 offset:4096
	ds_read_b128 v[64:67], v17 offset:8192
	ds_read_b128 v[102:105], v17 offset:12288
	ds_read_b128 v[106:109], v17 offset:16384
	ds_read_b128 v[110:113], v17 offset:20480
	ds_read_b128 v[114:117], v17 offset:24576
	ds_read_b128 v[120:123], v17 offset:28672
	ds_read_b128 v[124:127], v17 offset:32768
	s_waitcnt vmcnt(28) lgkmcnt(9)
	v_fmac_f32_e32 v6, v70, v46
	v_fmac_f32_e32 v7, v70, v18
	v_fmac_f32_e32 v10, v70, v22
	v_fmac_f32_e32 v11, v70, v26
	v_fmac_f32_e32 v12, v70, v30
	v_fmac_f32_e32 v13, v70, v34
	v_fmac_f32_e32 v14, v70, v38
	v_fmac_f32_e32 v15, v70, v42
	v_fmac_f32_e32 v8, v70, v50
	v_fmac_f32_e32 v6, v71, v47
	v_fmac_f32_e32 v7, v71, v19
	v_fmac_f32_e32 v10, v71, v23
	v_fmac_f32_e32 v11, v71, v27
	v_fmac_f32_e32 v12, v71, v31
	v_fmac_f32_e32 v13, v71, v35
	v_fmac_f32_e32 v14, v71, v39
	v_fmac_f32_e32 v15, v71, v43
	v_fmac_f32_e32 v8, v71, v51
	v_fmac_f32_e32 v6, v72, v48
	v_fmac_f32_e32 v7, v72, v20
	v_fmac_f32_e32 v10, v72, v24
	v_fmac_f32_e32 v11, v72, v28
	v_fmac_f32_e32 v12, v72, v32
	v_fmac_f32_e32 v13, v72, v36
	v_fmac_f32_e32 v14, v72, v40
	v_fmac_f32_e32 v15, v72, v44
	v_fmac_f32_e32 v8, v72, v52
	v_fmac_f32_e32 v6, v73, v49
	v_fmac_f32_e32 v7, v73, v21
	v_fmac_f32_e32 v10, v73, v25
	v_fmac_f32_e32 v11, v73, v29
	v_fmac_f32_e32 v12, v73, v33
	v_fmac_f32_e32 v13, v73, v37
	v_fmac_f32_e32 v14, v73, v41
	v_fmac_f32_e32 v15, v73, v45
	v_fmac_f32_e32 v8, v73, v53
	global_load_dword v70, v[54:55], off
	v_lshl_add_u64 v[54:55], v[54:55], 0, s[24:25]
	global_load_dword v71, v[54:55], off
	v_lshl_add_u64 v[54:55], v[54:55], 0, s[24:25]
	global_load_dword v72, v[54:55], off
	v_lshl_add_u64 v[54:55], v[54:55], 0, s[24:25]
	global_load_dword v73, v[54:55], off
	v_lshl_add_u64 v[54:55], v[54:55], 0, s[24:25]
	v_add_u32_e32 v17, 16, v17
	ds_read_b128 v[46:49], v17
	ds_read_b128 v[18:21], v17 offset:4096
	ds_read_b128 v[22:25], v17 offset:8192
	ds_read_b128 v[26:29], v17 offset:12288
	ds_read_b128 v[30:33], v17 offset:16384
	ds_read_b128 v[34:37], v17 offset:20480
	ds_read_b128 v[38:41], v17 offset:24576
	ds_read_b128 v[42:45], v17 offset:28672
	ds_read_b128 v[50:53], v17 offset:32768
	s_waitcnt vmcnt(28) lgkmcnt(9)
	v_fmac_f32_e32 v6, v74, v56
	v_fmac_f32_e32 v7, v74, v60
	v_fmac_f32_e32 v10, v74, v64
	v_fmac_f32_e32 v11, v74, v102
	v_fmac_f32_e32 v12, v74, v106
	v_fmac_f32_e32 v13, v74, v110
	v_fmac_f32_e32 v14, v74, v114
	v_fmac_f32_e32 v15, v74, v120
	v_fmac_f32_e32 v8, v74, v124
	v_fmac_f32_e32 v6, v75, v57
	v_fmac_f32_e32 v7, v75, v61
	v_fmac_f32_e32 v10, v75, v65
	v_fmac_f32_e32 v11, v75, v103
	v_fmac_f32_e32 v12, v75, v107
	v_fmac_f32_e32 v13, v75, v111
	v_fmac_f32_e32 v14, v75, v115
	v_fmac_f32_e32 v15, v75, v121
	v_fmac_f32_e32 v8, v75, v125
	v_fmac_f32_e32 v6, v76, v58
	v_fmac_f32_e32 v7, v76, v62
	v_fmac_f32_e32 v10, v76, v66
	v_fmac_f32_e32 v11, v76, v104
	v_fmac_f32_e32 v12, v76, v108
	v_fmac_f32_e32 v13, v76, v112
	v_fmac_f32_e32 v14, v76, v116
	v_fmac_f32_e32 v15, v76, v122
	v_fmac_f32_e32 v8, v76, v126
	v_fmac_f32_e32 v6, v77, v59
	v_fmac_f32_e32 v7, v77, v63
	v_fmac_f32_e32 v10, v77, v67
	v_fmac_f32_e32 v11, v77, v105
	v_fmac_f32_e32 v12, v77, v109
	v_fmac_f32_e32 v13, v77, v113
	v_fmac_f32_e32 v14, v77, v117
	v_fmac_f32_e32 v15, v77, v123
	v_fmac_f32_e32 v8, v77, v127
	global_load_dword v74, v[54:55], off
	v_lshl_add_u64 v[54:55], v[54:55], 0, s[24:25]
	global_load_dword v75, v[54:55], off
	v_lshl_add_u64 v[54:55], v[54:55], 0, s[24:25]
	global_load_dword v76, v[54:55], off
	v_lshl_add_u64 v[54:55], v[54:55], 0, s[24:25]
	global_load_dword v77, v[54:55], off
	v_lshl_add_u64 v[54:55], v[54:55], 0, s[24:25]
	v_add_u32_e32 v17, 16, v17
	ds_read_b128 v[56:59], v17
	ds_read_b128 v[60:63], v17 offset:4096
	ds_read_b128 v[64:67], v17 offset:8192
	ds_read_b128 v[102:105], v17 offset:12288
	ds_read_b128 v[106:109], v17 offset:16384
	ds_read_b128 v[110:113], v17 offset:20480
	ds_read_b128 v[114:117], v17 offset:24576
	ds_read_b128 v[120:123], v17 offset:28672
	ds_read_b128 v[124:127], v17 offset:32768
	s_waitcnt vmcnt(28) lgkmcnt(9)
	v_fmac_f32_e32 v6, v78, v46
	v_fmac_f32_e32 v7, v78, v18
	v_fmac_f32_e32 v10, v78, v22
	v_fmac_f32_e32 v11, v78, v26
	v_fmac_f32_e32 v12, v78, v30
	v_fmac_f32_e32 v13, v78, v34
	v_fmac_f32_e32 v14, v78, v38
	v_fmac_f32_e32 v15, v78, v42
	v_fmac_f32_e32 v8, v78, v50
	v_fmac_f32_e32 v6, v79, v47
	v_fmac_f32_e32 v7, v79, v19
	v_fmac_f32_e32 v10, v79, v23
	v_fmac_f32_e32 v11, v79, v27
	v_fmac_f32_e32 v12, v79, v31
	v_fmac_f32_e32 v13, v79, v35
	v_fmac_f32_e32 v14, v79, v39
	v_fmac_f32_e32 v15, v79, v43
	v_fmac_f32_e32 v8, v79, v51
	v_fmac_f32_e32 v6, v80, v48
	v_fmac_f32_e32 v7, v80, v20
	v_fmac_f32_e32 v10, v80, v24
	v_fmac_f32_e32 v11, v80, v28
	v_fmac_f32_e32 v12, v80, v32
	v_fmac_f32_e32 v13, v80, v36
	v_fmac_f32_e32 v14, v80, v40
	v_fmac_f32_e32 v15, v80, v44
	v_fmac_f32_e32 v8, v80, v52
	v_fmac_f32_e32 v6, v81, v49
	v_fmac_f32_e32 v7, v81, v21
	v_fmac_f32_e32 v10, v81, v25
	v_fmac_f32_e32 v11, v81, v29
	v_fmac_f32_e32 v12, v81, v33
	v_fmac_f32_e32 v13, v81, v37
	v_fmac_f32_e32 v14, v81, v41
	v_fmac_f32_e32 v15, v81, v45
	v_fmac_f32_e32 v8, v81, v53
	global_load_dword v78, v[54:55], off
	v_lshl_add_u64 v[54:55], v[54:55], 0, s[24:25]
	global_load_dword v79, v[54:55], off
	v_lshl_add_u64 v[54:55], v[54:55], 0, s[24:25]
	global_load_dword v80, v[54:55], off
	v_lshl_add_u64 v[54:55], v[54:55], 0, s[24:25]
	global_load_dword v81, v[54:55], off
	v_lshl_add_u64 v[54:55], v[54:55], 0, s[24:25]
	v_add_u32_e32 v17, 16, v17
	ds_read_b128 v[46:49], v17
	ds_read_b128 v[18:21], v17 offset:4096
	ds_read_b128 v[22:25], v17 offset:8192
	ds_read_b128 v[26:29], v17 offset:12288
	ds_read_b128 v[30:33], v17 offset:16384
	ds_read_b128 v[34:37], v17 offset:20480
	ds_read_b128 v[38:41], v17 offset:24576
	ds_read_b128 v[42:45], v17 offset:28672
	ds_read_b128 v[50:53], v17 offset:32768
	s_waitcnt vmcnt(28) lgkmcnt(9)
	v_fmac_f32_e32 v6, v82, v56
	v_fmac_f32_e32 v7, v82, v60
	v_fmac_f32_e32 v10, v82, v64
	v_fmac_f32_e32 v11, v82, v102
	v_fmac_f32_e32 v12, v82, v106
	v_fmac_f32_e32 v13, v82, v110
	v_fmac_f32_e32 v14, v82, v114
	v_fmac_f32_e32 v15, v82, v120
	v_fmac_f32_e32 v8, v82, v124
	v_fmac_f32_e32 v6, v83, v57
	v_fmac_f32_e32 v7, v83, v61
	v_fmac_f32_e32 v10, v83, v65
	v_fmac_f32_e32 v11, v83, v103
	v_fmac_f32_e32 v12, v83, v107
	v_fmac_f32_e32 v13, v83, v111
	v_fmac_f32_e32 v14, v83, v115
	v_fmac_f32_e32 v15, v83, v121
	v_fmac_f32_e32 v8, v83, v125
	v_fmac_f32_e32 v6, v84, v58
	v_fmac_f32_e32 v7, v84, v62
	v_fmac_f32_e32 v10, v84, v66
	v_fmac_f32_e32 v11, v84, v104
	v_fmac_f32_e32 v12, v84, v108
	v_fmac_f32_e32 v13, v84, v112
	v_fmac_f32_e32 v14, v84, v116
	v_fmac_f32_e32 v15, v84, v122
	v_fmac_f32_e32 v8, v84, v126
	v_fmac_f32_e32 v6, v85, v59
	v_fmac_f32_e32 v7, v85, v63
	v_fmac_f32_e32 v10, v85, v67
	v_fmac_f32_e32 v11, v85, v105
	v_fmac_f32_e32 v12, v85, v109
	v_fmac_f32_e32 v13, v85, v113
	v_fmac_f32_e32 v14, v85, v117
	v_fmac_f32_e32 v15, v85, v123
	v_fmac_f32_e32 v8, v85, v127
	global_load_dword v82, v[54:55], off
	v_lshl_add_u64 v[54:55], v[54:55], 0, s[24:25]
	global_load_dword v83, v[54:55], off
	v_lshl_add_u64 v[54:55], v[54:55], 0, s[24:25]
	global_load_dword v84, v[54:55], off
	v_lshl_add_u64 v[54:55], v[54:55], 0, s[24:25]
	global_load_dword v85, v[54:55], off
	v_lshl_add_u64 v[54:55], v[54:55], 0, s[24:25]
	v_add_u32_e32 v17, 16, v17
	ds_read_b128 v[56:59], v17
	ds_read_b128 v[60:63], v17 offset:4096
	ds_read_b128 v[64:67], v17 offset:8192
	ds_read_b128 v[102:105], v17 offset:12288
	ds_read_b128 v[106:109], v17 offset:16384
	ds_read_b128 v[110:113], v17 offset:20480
	ds_read_b128 v[114:117], v17 offset:24576
	ds_read_b128 v[120:123], v17 offset:28672
	ds_read_b128 v[124:127], v17 offset:32768
	s_waitcnt vmcnt(28) lgkmcnt(9)
	v_fmac_f32_e32 v6, v86, v46
	v_fmac_f32_e32 v7, v86, v18
	v_fmac_f32_e32 v10, v86, v22
	v_fmac_f32_e32 v11, v86, v26
	v_fmac_f32_e32 v12, v86, v30
	v_fmac_f32_e32 v13, v86, v34
	v_fmac_f32_e32 v14, v86, v38
	v_fmac_f32_e32 v15, v86, v42
	v_fmac_f32_e32 v8, v86, v50
	v_fmac_f32_e32 v6, v87, v47
	v_fmac_f32_e32 v7, v87, v19
	v_fmac_f32_e32 v10, v87, v23
	v_fmac_f32_e32 v11, v87, v27
	v_fmac_f32_e32 v12, v87, v31
	v_fmac_f32_e32 v13, v87, v35
	v_fmac_f32_e32 v14, v87, v39
	v_fmac_f32_e32 v15, v87, v43
	v_fmac_f32_e32 v8, v87, v51
	v_fmac_f32_e32 v6, v88, v48
	v_fmac_f32_e32 v7, v88, v20
	v_fmac_f32_e32 v10, v88, v24
	v_fmac_f32_e32 v11, v88, v28
	v_fmac_f32_e32 v12, v88, v32
	v_fmac_f32_e32 v13, v88, v36
	v_fmac_f32_e32 v14, v88, v40
	v_fmac_f32_e32 v15, v88, v44
	v_fmac_f32_e32 v8, v88, v52
	v_fmac_f32_e32 v6, v89, v49
	v_fmac_f32_e32 v7, v89, v21
	v_fmac_f32_e32 v10, v89, v25
	v_fmac_f32_e32 v11, v89, v29
	v_fmac_f32_e32 v12, v89, v33
	v_fmac_f32_e32 v13, v89, v37
	v_fmac_f32_e32 v14, v89, v41
	v_fmac_f32_e32 v15, v89, v45
	v_fmac_f32_e32 v8, v89, v53
	global_load_dword v86, v[54:55], off
	v_lshl_add_u64 v[54:55], v[54:55], 0, s[24:25]
	global_load_dword v87, v[54:55], off
	v_lshl_add_u64 v[54:55], v[54:55], 0, s[24:25]
	global_load_dword v88, v[54:55], off
	v_lshl_add_u64 v[54:55], v[54:55], 0, s[24:25]
	global_load_dword v89, v[54:55], off
	v_lshl_add_u64 v[54:55], v[54:55], 0, s[24:25]
	v_add_u32_e32 v17, 16, v17
	ds_read_b128 v[46:49], v17
	ds_read_b128 v[18:21], v17 offset:4096
	ds_read_b128 v[22:25], v17 offset:8192
	ds_read_b128 v[26:29], v17 offset:12288
	ds_read_b128 v[30:33], v17 offset:16384
	ds_read_b128 v[34:37], v17 offset:20480
	ds_read_b128 v[38:41], v17 offset:24576
	ds_read_b128 v[42:45], v17 offset:28672
	ds_read_b128 v[50:53], v17 offset:32768
	s_waitcnt vmcnt(28) lgkmcnt(9)
	v_fmac_f32_e32 v6, v90, v56
	v_fmac_f32_e32 v7, v90, v60
	v_fmac_f32_e32 v10, v90, v64
	v_fmac_f32_e32 v11, v90, v102
	v_fmac_f32_e32 v12, v90, v106
	v_fmac_f32_e32 v13, v90, v110
	v_fmac_f32_e32 v14, v90, v114
	v_fmac_f32_e32 v15, v90, v120
	v_fmac_f32_e32 v8, v90, v124
	v_fmac_f32_e32 v6, v91, v57
	v_fmac_f32_e32 v7, v91, v61
	v_fmac_f32_e32 v10, v91, v65
	v_fmac_f32_e32 v11, v91, v103
	v_fmac_f32_e32 v12, v91, v107
	v_fmac_f32_e32 v13, v91, v111
	v_fmac_f32_e32 v14, v91, v115
	v_fmac_f32_e32 v15, v91, v121
	v_fmac_f32_e32 v8, v91, v125
	v_fmac_f32_e32 v6, v92, v58
	v_fmac_f32_e32 v7, v92, v62
	v_fmac_f32_e32 v10, v92, v66
	v_fmac_f32_e32 v11, v92, v104
	v_fmac_f32_e32 v12, v92, v108
	v_fmac_f32_e32 v13, v92, v112
	v_fmac_f32_e32 v14, v92, v116
	v_fmac_f32_e32 v15, v92, v122
	v_fmac_f32_e32 v8, v92, v126
	v_fmac_f32_e32 v6, v93, v59
	v_fmac_f32_e32 v7, v93, v63
	v_fmac_f32_e32 v10, v93, v67
	v_fmac_f32_e32 v11, v93, v105
	v_fmac_f32_e32 v12, v93, v109
	v_fmac_f32_e32 v13, v93, v113
	v_fmac_f32_e32 v14, v93, v117
	v_fmac_f32_e32 v15, v93, v123
	v_fmac_f32_e32 v8, v93, v127
	global_load_dword v90, v[54:55], off
	v_lshl_add_u64 v[54:55], v[54:55], 0, s[24:25]
	global_load_dword v91, v[54:55], off
	v_lshl_add_u64 v[54:55], v[54:55], 0, s[24:25]
	global_load_dword v92, v[54:55], off
	v_lshl_add_u64 v[54:55], v[54:55], 0, s[24:25]
	global_load_dword v93, v[54:55], off
	v_lshl_add_u64 v[54:55], v[54:55], 0, s[24:25]
	v_add_u32_e32 v17, 16, v17
	ds_read_b128 v[56:59], v17
	ds_read_b128 v[60:63], v17 offset:4096
	ds_read_b128 v[64:67], v17 offset:8192
	ds_read_b128 v[102:105], v17 offset:12288
	ds_read_b128 v[106:109], v17 offset:16384
	ds_read_b128 v[110:113], v17 offset:20480
	ds_read_b128 v[114:117], v17 offset:24576
	ds_read_b128 v[120:123], v17 offset:28672
	ds_read_b128 v[124:127], v17 offset:32768
	s_waitcnt vmcnt(28) lgkmcnt(9)
	v_fmac_f32_e32 v6, v94, v46
	v_fmac_f32_e32 v7, v94, v18
	v_fmac_f32_e32 v10, v94, v22
	v_fmac_f32_e32 v11, v94, v26
	v_fmac_f32_e32 v12, v94, v30
	v_fmac_f32_e32 v13, v94, v34
	v_fmac_f32_e32 v14, v94, v38
	v_fmac_f32_e32 v15, v94, v42
	v_fmac_f32_e32 v8, v94, v50
	v_fmac_f32_e32 v6, v95, v47
	v_fmac_f32_e32 v7, v95, v19
	v_fmac_f32_e32 v10, v95, v23
	v_fmac_f32_e32 v11, v95, v27
	v_fmac_f32_e32 v12, v95, v31
	v_fmac_f32_e32 v13, v95, v35
	v_fmac_f32_e32 v14, v95, v39
	v_fmac_f32_e32 v15, v95, v43
	v_fmac_f32_e32 v8, v95, v51
	v_fmac_f32_e32 v6, v96, v48
	v_fmac_f32_e32 v7, v96, v20
	v_fmac_f32_e32 v10, v96, v24
	v_fmac_f32_e32 v11, v96, v28
	v_fmac_f32_e32 v12, v96, v32
	v_fmac_f32_e32 v13, v96, v36
	v_fmac_f32_e32 v14, v96, v40
	v_fmac_f32_e32 v15, v96, v44
	v_fmac_f32_e32 v8, v96, v52
	v_fmac_f32_e32 v6, v97, v49
	v_fmac_f32_e32 v7, v97, v21
	v_fmac_f32_e32 v10, v97, v25
	v_fmac_f32_e32 v11, v97, v29
	v_fmac_f32_e32 v12, v97, v33
	v_fmac_f32_e32 v13, v97, v37
	v_fmac_f32_e32 v14, v97, v41
	v_fmac_f32_e32 v15, v97, v45
	v_fmac_f32_e32 v8, v97, v53
	global_load_dword v94, v[54:55], off
	v_lshl_add_u64 v[54:55], v[54:55], 0, s[24:25]
	global_load_dword v95, v[54:55], off
	v_lshl_add_u64 v[54:55], v[54:55], 0, s[24:25]
	global_load_dword v96, v[54:55], off
	v_lshl_add_u64 v[54:55], v[54:55], 0, s[24:25]
	global_load_dword v97, v[54:55], off
	v_lshl_add_u64 v[54:55], v[54:55], 0, s[24:25]
	v_add_u32_e32 v17, 16, v17
	ds_read_b128 v[46:49], v17
	ds_read_b128 v[18:21], v17 offset:4096
	ds_read_b128 v[22:25], v17 offset:8192
	ds_read_b128 v[26:29], v17 offset:12288
	ds_read_b128 v[30:33], v17 offset:16384
	ds_read_b128 v[34:37], v17 offset:20480
	ds_read_b128 v[38:41], v17 offset:24576
	ds_read_b128 v[42:45], v17 offset:28672
	ds_read_b128 v[50:53], v17 offset:32768
	s_waitcnt vmcnt(28) lgkmcnt(9)
	v_fmac_f32_e32 v6, v98, v56
	v_fmac_f32_e32 v7, v98, v60
	v_fmac_f32_e32 v10, v98, v64
	v_fmac_f32_e32 v11, v98, v102
	v_fmac_f32_e32 v12, v98, v106
	v_fmac_f32_e32 v13, v98, v110
	v_fmac_f32_e32 v14, v98, v114
	v_fmac_f32_e32 v15, v98, v120
	v_fmac_f32_e32 v8, v98, v124
	v_fmac_f32_e32 v6, v99, v57
	v_fmac_f32_e32 v7, v99, v61
	v_fmac_f32_e32 v10, v99, v65
	v_fmac_f32_e32 v11, v99, v103
	v_fmac_f32_e32 v12, v99, v107
	v_fmac_f32_e32 v13, v99, v111
	v_fmac_f32_e32 v14, v99, v115
	v_fmac_f32_e32 v15, v99, v121
	v_fmac_f32_e32 v8, v99, v125
	v_fmac_f32_e32 v6, v100, v58
	v_fmac_f32_e32 v7, v100, v62
	v_fmac_f32_e32 v10, v100, v66
	v_fmac_f32_e32 v11, v100, v104
	v_fmac_f32_e32 v12, v100, v108
	v_fmac_f32_e32 v13, v100, v112
	v_fmac_f32_e32 v14, v100, v116
	v_fmac_f32_e32 v15, v100, v122
	v_fmac_f32_e32 v8, v100, v126
	v_fmac_f32_e32 v6, v101, v59
	v_fmac_f32_e32 v7, v101, v63
	v_fmac_f32_e32 v10, v101, v67
	v_fmac_f32_e32 v11, v101, v105
	v_fmac_f32_e32 v12, v101, v109
	v_fmac_f32_e32 v13, v101, v113
	v_fmac_f32_e32 v14, v101, v117
	v_fmac_f32_e32 v15, v101, v123
	v_fmac_f32_e32 v8, v101, v127
	global_load_dword v98, v[54:55], off
	v_lshl_add_u64 v[54:55], v[54:55], 0, s[24:25]
	global_load_dword v99, v[54:55], off
	v_lshl_add_u64 v[54:55], v[54:55], 0, s[24:25]
	global_load_dword v100, v[54:55], off
	v_lshl_add_u64 v[54:55], v[54:55], 0, s[24:25]
	global_load_dword v101, v[54:55], off
	v_lshl_add_u64 v[54:55], v[54:55], 0, s[24:25]
	s_sub_i32 s4, s4, 1
	s_cmp_lg_u32 s4, 0
	s_cbranch_scc1 .Lada_loop
	v_add_u32_e32 v17, 16, v17
	ds_read_b128 v[56:59], v17
	ds_read_b128 v[60:63], v17 offset:4096
	ds_read_b128 v[64:67], v17 offset:8192
	ds_read_b128 v[102:105], v17 offset:12288
	ds_read_b128 v[106:109], v17 offset:16384
	ds_read_b128 v[110:113], v17 offset:20480
	ds_read_b128 v[114:117], v17 offset:24576
	ds_read_b128 v[120:123], v17 offset:28672
	ds_read_b128 v[124:127], v17 offset:32768
	s_waitcnt vmcnt(28) lgkmcnt(9)
	v_fmac_f32_e32 v6, v70, v46
	v_fmac_f32_e32 v7, v70, v18
	v_fmac_f32_e32 v10, v70, v22
	v_fmac_f32_e32 v11, v70, v26
	v_fmac_f32_e32 v12, v70, v30
	v_fmac_f32_e32 v13, v70, v34
	v_fmac_f32_e32 v14, v70, v38
	v_fmac_f32_e32 v15, v70, v42
	v_fmac_f32_e32 v8, v70, v50
	v_fmac_f32_e32 v6, v71, v47
	v_fmac_f32_e32 v7, v71, v19
	v_fmac_f32_e32 v10, v71, v23
	v_fmac_f32_e32 v11, v71, v27
	v_fmac_f32_e32 v12, v71, v31
	v_fmac_f32_e32 v13, v71, v35
	v_fmac_f32_e32 v14, v71, v39
	v_fmac_f32_e32 v15, v71, v43
	v_fmac_f32_e32 v8, v71, v51
	v_fmac_f32_e32 v6, v72, v48
	v_fmac_f32_e32 v7, v72, v20
	v_fmac_f32_e32 v10, v72, v24
	v_fmac_f32_e32 v11, v72, v28
	v_fmac_f32_e32 v12, v72, v32
	v_fmac_f32_e32 v13, v72, v36
	v_fmac_f32_e32 v14, v72, v40
	v_fmac_f32_e32 v15, v72, v44
	v_fmac_f32_e32 v8, v72, v52
	v_fmac_f32_e32 v6, v73, v49
	v_fmac_f32_e32 v7, v73, v21
	v_fmac_f32_e32 v10, v73, v25
	v_fmac_f32_e32 v11, v73, v29
	v_fmac_f32_e32 v12, v73, v33
	v_fmac_f32_e32 v13, v73, v37
	v_fmac_f32_e32 v14, v73, v41
	v_fmac_f32_e32 v15, v73, v45
	v_fmac_f32_e32 v8, v73, v53
	v_add_u32_e32 v17, 16, v17
	ds_read_b128 v[46:49], v17
	ds_read_b128 v[18:21], v17 offset:4096
	ds_read_b128 v[22:25], v17 offset:8192
	ds_read_b128 v[26:29], v17 offset:12288
	ds_read_b128 v[30:33], v17 offset:16384
	ds_read_b128 v[34:37], v17 offset:20480
	ds_read_b128 v[38:41], v17 offset:24576
	ds_read_b128 v[42:45], v17 offset:28672
	ds_read_b128 v[50:53], v17 offset:32768
	s_waitcnt vmcnt(24) lgkmcnt(9)
	v_fmac_f32_e32 v6, v74, v56
	v_fmac_f32_e32 v7, v74, v60
	v_fmac_f32_e32 v10, v74, v64
	v_fmac_f32_e32 v11, v74, v102
	v_fmac_f32_e32 v12, v74, v106
	v_fmac_f32_e32 v13, v74, v110
	v_fmac_f32_e32 v14, v74, v114
	v_fmac_f32_e32 v15, v74, v120
	v_fmac_f32_e32 v8, v74, v124
	v_fmac_f32_e32 v6, v75, v57
	v_fmac_f32_e32 v7, v75, v61
	v_fmac_f32_e32 v10, v75, v65
	v_fmac_f32_e32 v11, v75, v103
	v_fmac_f32_e32 v12, v75, v107
	v_fmac_f32_e32 v13, v75, v111
	v_fmac_f32_e32 v14, v75, v115
	v_fmac_f32_e32 v15, v75, v121
	v_fmac_f32_e32 v8, v75, v125
	v_fmac_f32_e32 v6, v76, v58
	v_fmac_f32_e32 v7, v76, v62
	v_fmac_f32_e32 v10, v76, v66
	v_fmac_f32_e32 v11, v76, v104
	v_fmac_f32_e32 v12, v76, v108
	v_fmac_f32_e32 v13, v76, v112
	v_fmac_f32_e32 v14, v76, v116
	v_fmac_f32_e32 v15, v76, v122
	v_fmac_f32_e32 v8, v76, v126
	v_fmac_f32_e32 v6, v77, v59
	v_fmac_f32_e32 v7, v77, v63
	v_fmac_f32_e32 v10, v77, v67
	v_fmac_f32_e32 v11, v77, v105
	v_fmac_f32_e32 v12, v77, v109
	v_fmac_f32_e32 v13, v77, v113
	v_fmac_f32_e32 v14, v77, v117
	v_fmac_f32_e32 v15, v77, v123
	v_fmac_f32_e32 v8, v77, v127
	v_add_u32_e32 v17, 16, v17
	ds_read_b128 v[56:59], v17
	ds_read_b128 v[60:63], v17 offset:4096
	ds_read_b128 v[64:67], v17 offset:8192
	ds_read_b128 v[102:105], v17 offset:12288
	ds_read_b128 v[106:109], v17 offset:16384
	ds_read_b128 v[110:113], v17 offset:20480
	ds_read_b128 v[114:117], v17 offset:24576
	ds_read_b128 v[120:123], v17 offset:28672
	ds_read_b128 v[124:127], v17 offset:32768
	s_waitcnt vmcnt(20) lgkmcnt(9)
	v_fmac_f32_e32 v6, v78, v46
	v_fmac_f32_e32 v7, v78, v18
	v_fmac_f32_e32 v10, v78, v22
	v_fmac_f32_e32 v11, v78, v26
	v_fmac_f32_e32 v12, v78, v30
	v_fmac_f32_e32 v13, v78, v34
	v_fmac_f32_e32 v14, v78, v38
	v_fmac_f32_e32 v15, v78, v42
	v_fmac_f32_e32 v8, v78, v50
	v_fmac_f32_e32 v6, v79, v47
	v_fmac_f32_e32 v7, v79, v19
	v_fmac_f32_e32 v10, v79, v23
	v_fmac_f32_e32 v11, v79, v27
	v_fmac_f32_e32 v12, v79, v31
	v_fmac_f32_e32 v13, v79, v35
	v_fmac_f32_e32 v14, v79, v39
	v_fmac_f32_e32 v15, v79, v43
	v_fmac_f32_e32 v8, v79, v51
	v_fmac_f32_e32 v6, v80, v48
	v_fmac_f32_e32 v7, v80, v20
	v_fmac_f32_e32 v10, v80, v24
	v_fmac_f32_e32 v11, v80, v28
	v_fmac_f32_e32 v12, v80, v32
	v_fmac_f32_e32 v13, v80, v36
	v_fmac_f32_e32 v14, v80, v40
	v_fmac_f32_e32 v15, v80, v44
	v_fmac_f32_e32 v8, v80, v52
	v_fmac_f32_e32 v6, v81, v49
	v_fmac_f32_e32 v7, v81, v21
	v_fmac_f32_e32 v10, v81, v25
	v_fmac_f32_e32 v11, v81, v29
	v_fmac_f32_e32 v12, v81, v33
	v_fmac_f32_e32 v13, v81, v37
	v_fmac_f32_e32 v14, v81, v41
	v_fmac_f32_e32 v15, v81, v45
	v_fmac_f32_e32 v8, v81, v53
	v_add_u32_e32 v17, 16, v17
	ds_read_b128 v[46:49], v17
	ds_read_b128 v[18:21], v17 offset:4096
	ds_read_b128 v[22:25], v17 offset:8192
	ds_read_b128 v[26:29], v17 offset:12288
	ds_read_b128 v[30:33], v17 offset:16384
	ds_read_b128 v[34:37], v17 offset:20480
	ds_read_b128 v[38:41], v17 offset:24576
	ds_read_b128 v[42:45], v17 offset:28672
	ds_read_b128 v[50:53], v17 offset:32768
	s_waitcnt vmcnt(16) lgkmcnt(9)
	v_fmac_f32_e32 v6, v82, v56
	v_fmac_f32_e32 v7, v82, v60
	v_fmac_f32_e32 v10, v82, v64
	v_fmac_f32_e32 v11, v82, v102
	v_fmac_f32_e32 v12, v82, v106
	v_fmac_f32_e32 v13, v82, v110
	v_fmac_f32_e32 v14, v82, v114
	v_fmac_f32_e32 v15, v82, v120
	v_fmac_f32_e32 v8, v82, v124
	v_fmac_f32_e32 v6, v83, v57
	v_fmac_f32_e32 v7, v83, v61
	v_fmac_f32_e32 v10, v83, v65
	v_fmac_f32_e32 v11, v83, v103
	v_fmac_f32_e32 v12, v83, v107
	v_fmac_f32_e32 v13, v83, v111
	v_fmac_f32_e32 v14, v83, v115
	v_fmac_f32_e32 v15, v83, v121
	v_fmac_f32_e32 v8, v83, v125
	v_fmac_f32_e32 v6, v84, v58
	v_fmac_f32_e32 v7, v84, v62
	v_fmac_f32_e32 v10, v84, v66
	v_fmac_f32_e32 v11, v84, v104
	v_fmac_f32_e32 v12, v84, v108
	v_fmac_f32_e32 v13, v84, v112
	v_fmac_f32_e32 v14, v84, v116
	v_fmac_f32_e32 v15, v84, v122
	v_fmac_f32_e32 v8, v84, v126
	v_fmac_f32_e32 v6, v85, v59
	v_fmac_f32_e32 v7, v85, v63
	v_fmac_f32_e32 v10, v85, v67
	v_fmac_f32_e32 v11, v85, v105
	v_fmac_f32_e32 v12, v85, v109
	v_fmac_f32_e32 v13, v85, v113
	v_fmac_f32_e32 v14, v85, v117
	v_fmac_f32_e32 v15, v85, v123
	v_fmac_f32_e32 v8, v85, v127
	v_add_u32_e32 v17, 16, v17
	ds_read_b128 v[56:59], v17
	ds_read_b128 v[60:63], v17 offset:4096
	ds_read_b128 v[64:67], v17 offset:8192
	ds_read_b128 v[102:105], v17 offset:12288
	ds_read_b128 v[106:109], v17 offset:16384
	ds_read_b128 v[110:113], v17 offset:20480
	ds_read_b128 v[114:117], v17 offset:24576
	ds_read_b128 v[120:123], v17 offset:28672
	ds_read_b128 v[124:127], v17 offset:32768
	s_waitcnt vmcnt(12) lgkmcnt(9)
	v_fmac_f32_e32 v6, v86, v46
	v_fmac_f32_e32 v7, v86, v18
	v_fmac_f32_e32 v10, v86, v22
	v_fmac_f32_e32 v11, v86, v26
	v_fmac_f32_e32 v12, v86, v30
	v_fmac_f32_e32 v13, v86, v34
	v_fmac_f32_e32 v14, v86, v38
	v_fmac_f32_e32 v15, v86, v42
	v_fmac_f32_e32 v8, v86, v50
	v_fmac_f32_e32 v6, v87, v47
	v_fmac_f32_e32 v7, v87, v19
	v_fmac_f32_e32 v10, v87, v23
	v_fmac_f32_e32 v11, v87, v27
	v_fmac_f32_e32 v12, v87, v31
	v_fmac_f32_e32 v13, v87, v35
	v_fmac_f32_e32 v14, v87, v39
	v_fmac_f32_e32 v15, v87, v43
	v_fmac_f32_e32 v8, v87, v51
	v_fmac_f32_e32 v6, v88, v48
	v_fmac_f32_e32 v7, v88, v20
	v_fmac_f32_e32 v10, v88, v24
	v_fmac_f32_e32 v11, v88, v28
	v_fmac_f32_e32 v12, v88, v32
	v_fmac_f32_e32 v13, v88, v36
	v_fmac_f32_e32 v14, v88, v40
	v_fmac_f32_e32 v15, v88, v44
	v_fmac_f32_e32 v8, v88, v52
	v_fmac_f32_e32 v6, v89, v49
	v_fmac_f32_e32 v7, v89, v21
	v_fmac_f32_e32 v10, v89, v25
	v_fmac_f32_e32 v11, v89, v29
	v_fmac_f32_e32 v12, v89, v33
	v_fmac_f32_e32 v13, v89, v37
	v_fmac_f32_e32 v14, v89, v41
	v_fmac_f32_e32 v15, v89, v45
	v_fmac_f32_e32 v8, v89, v53
	v_add_u32_e32 v17, 16, v17
	ds_read_b128 v[46:49], v17
	ds_read_b128 v[18:21], v17 offset:4096
	ds_read_b128 v[22:25], v17 offset:8192
	ds_read_b128 v[26:29], v17 offset:12288
	ds_read_b128 v[30:33], v17 offset:16384
	ds_read_b128 v[34:37], v17 offset:20480
	ds_read_b128 v[38:41], v17 offset:24576
	ds_read_b128 v[42:45], v17 offset:28672
	ds_read_b128 v[50:53], v17 offset:32768
	s_waitcnt vmcnt(8) lgkmcnt(9)
	v_fmac_f32_e32 v6, v90, v56
	v_fmac_f32_e32 v7, v90, v60
	v_fmac_f32_e32 v10, v90, v64
	v_fmac_f32_e32 v11, v90, v102
	v_fmac_f32_e32 v12, v90, v106
	v_fmac_f32_e32 v13, v90, v110
	v_fmac_f32_e32 v14, v90, v114
	v_fmac_f32_e32 v15, v90, v120
	v_fmac_f32_e32 v8, v90, v124
	v_fmac_f32_e32 v6, v91, v57
	v_fmac_f32_e32 v7, v91, v61
	v_fmac_f32_e32 v10, v91, v65
	v_fmac_f32_e32 v11, v91, v103
	v_fmac_f32_e32 v12, v91, v107
	v_fmac_f32_e32 v13, v91, v111
	v_fmac_f32_e32 v14, v91, v115
	v_fmac_f32_e32 v15, v91, v121
	v_fmac_f32_e32 v8, v91, v125
	v_fmac_f32_e32 v6, v92, v58
	v_fmac_f32_e32 v7, v92, v62
	v_fmac_f32_e32 v10, v92, v66
	v_fmac_f32_e32 v11, v92, v104
	v_fmac_f32_e32 v12, v92, v108
	v_fmac_f32_e32 v13, v92, v112
	v_fmac_f32_e32 v14, v92, v116
	v_fmac_f32_e32 v15, v92, v122
	v_fmac_f32_e32 v8, v92, v126
	v_fmac_f32_e32 v6, v93, v59
	v_fmac_f32_e32 v7, v93, v63
	v_fmac_f32_e32 v10, v93, v67
	v_fmac_f32_e32 v11, v93, v105
	v_fmac_f32_e32 v12, v93, v109
	v_fmac_f32_e32 v13, v93, v113
	v_fmac_f32_e32 v14, v93, v117
	v_fmac_f32_e32 v15, v93, v123
	v_fmac_f32_e32 v8, v93, v127
	v_add_u32_e32 v17, 16, v17
	ds_read_b128 v[56:59], v17
	ds_read_b128 v[60:63], v17 offset:4096
	ds_read_b128 v[64:67], v17 offset:8192
	ds_read_b128 v[102:105], v17 offset:12288
	ds_read_b128 v[106:109], v17 offset:16384
	ds_read_b128 v[110:113], v17 offset:20480
	ds_read_b128 v[114:117], v17 offset:24576
	ds_read_b128 v[120:123], v17 offset:28672
	ds_read_b128 v[124:127], v17 offset:32768
	s_waitcnt vmcnt(4) lgkmcnt(9)
	v_fmac_f32_e32 v6, v94, v46
	v_fmac_f32_e32 v7, v94, v18
	v_fmac_f32_e32 v10, v94, v22
	v_fmac_f32_e32 v11, v94, v26
	v_fmac_f32_e32 v12, v94, v30
	v_fmac_f32_e32 v13, v94, v34
	v_fmac_f32_e32 v14, v94, v38
	v_fmac_f32_e32 v15, v94, v42
	v_fmac_f32_e32 v8, v94, v50
	v_fmac_f32_e32 v6, v95, v47
	v_fmac_f32_e32 v7, v95, v19
	v_fmac_f32_e32 v10, v95, v23
	v_fmac_f32_e32 v11, v95, v27
	v_fmac_f32_e32 v12, v95, v31
	v_fmac_f32_e32 v13, v95, v35
	v_fmac_f32_e32 v14, v95, v39
	v_fmac_f32_e32 v15, v95, v43
	v_fmac_f32_e32 v8, v95, v51
	v_fmac_f32_e32 v6, v96, v48
	v_fmac_f32_e32 v7, v96, v20
	v_fmac_f32_e32 v10, v96, v24
	v_fmac_f32_e32 v11, v96, v28
	v_fmac_f32_e32 v12, v96, v32
	v_fmac_f32_e32 v13, v96, v36
	v_fmac_f32_e32 v14, v96, v40
	v_fmac_f32_e32 v15, v96, v44
	v_fmac_f32_e32 v8, v96, v52
	v_fmac_f32_e32 v6, v97, v49
	v_fmac_f32_e32 v7, v97, v21
	v_fmac_f32_e32 v10, v97, v25
	v_fmac_f32_e32 v11, v97, v29
	v_fmac_f32_e32 v12, v97, v33
	v_fmac_f32_e32 v13, v97, v37
	v_fmac_f32_e32 v14, v97, v41
	v_fmac_f32_e32 v15, v97, v45
	v_fmac_f32_e32 v8, v97, v53
	s_waitcnt vmcnt(0) lgkmcnt(0)
	v_fmac_f32_e32 v6, v98, v56
	v_fmac_f32_e32 v7, v98, v60
	v_fmac_f32_e32 v10, v98, v64
	v_fmac_f32_e32 v11, v98, v102
	v_fmac_f32_e32 v12, v98, v106
	v_fmac_f32_e32 v13, v98, v110
	v_fmac_f32_e32 v14, v98, v114
	v_fmac_f32_e32 v15, v98, v120
	v_fmac_f32_e32 v8, v98, v124
	v_fmac_f32_e32 v6, v99, v57
	v_fmac_f32_e32 v7, v99, v61
	v_fmac_f32_e32 v10, v99, v65
	v_fmac_f32_e32 v11, v99, v103
	v_fmac_f32_e32 v12, v99, v107
	v_fmac_f32_e32 v13, v99, v111
	v_fmac_f32_e32 v14, v99, v115
	v_fmac_f32_e32 v15, v99, v121
	v_fmac_f32_e32 v8, v99, v125
	v_fmac_f32_e32 v6, v100, v58
	v_fmac_f32_e32 v7, v100, v62
	v_fmac_f32_e32 v10, v100, v66
	v_fmac_f32_e32 v11, v100, v104
	v_fmac_f32_e32 v12, v100, v108
	v_fmac_f32_e32 v13, v100, v112
	v_fmac_f32_e32 v14, v100, v116
	v_fmac_f32_e32 v15, v100, v122
	v_fmac_f32_e32 v8, v100, v126
	v_fmac_f32_e32 v6, v101, v59
	v_fmac_f32_e32 v7, v101, v63
	v_fmac_f32_e32 v10, v101, v67
	v_fmac_f32_e32 v11, v101, v105
	v_fmac_f32_e32 v12, v101, v109
	v_fmac_f32_e32 v13, v101, v113
	v_fmac_f32_e32 v14, v101, v117
	v_fmac_f32_e32 v15, v101, v123
	v_fmac_f32_e32 v8, v101, v127
	v_add_u32_e32 v4, s6, v16
	ds_write2st64_b32 v4, v6, v7 offset0:144 offset1:145
	ds_write2st64_b32 v4, v10, v11 offset0:146 offset1:147
	ds_write2st64_b32 v4, v12, v13 offset0:148 offset1:149
	ds_write2st64_b32 v4, v14, v15 offset0:150 offset1:151
	ds_write_b32 v4, v8 offset:38912
	s_waitcnt lgkmcnt(0)
	s_barrier
	s_and_saveexec_b64 s[4:5], vcc
	s_movk_i32 s24, 0xc00
	s_cbranch_execz .LBB0_563
	s_mul_i32 s0, s19, 0xc00
	s_add_i32 s0, s0, s2
	v_or_b32_e32 v4, s0, v1
	v_readlane_b32 s48, v253, 32
	v_ashrrev_i32_e32 v5, 31, v4
	v_readlane_b32 s58, v253, 42
	v_readlane_b32 s59, v253, 43
	s_mul_i32 s19, s19, 9
	v_or_b32_e32 v6, s2, v1
	v_lshl_add_u64 v[4:5], v[4:5], 2, s[58:59]
	s_mov_b64 s[2:3], 0
	v_mov_b32_e32 v7, v0
	v_readlane_b32 s49, v253, 33
	v_readlane_b32 s50, v253, 34
	v_readlane_b32 s51, v253, 35
	v_readlane_b32 s52, v253, 36
	v_readlane_b32 s53, v253, 37
	v_readlane_b32 s54, v253, 38
	v_readlane_b32 s55, v253, 39
	v_readlane_b32 s56, v253, 40
	v_readlane_b32 s57, v253, 41
	v_readlane_b32 s60, v253, 44
	v_readlane_b32 s61, v253, 45
	v_readlane_b32 s62, v253, 46
	v_readlane_b32 s63, v253, 47
